# FFN-down halo fix-up loop: all 26 halo-row loads of an iteration issued up front (SGPR base + constant form) behind one wait; store wait dropped
# baseline (speedup 1.0000x reference)
.LBB0_289:
	s_add_u32 s100, s30, 0x3000
	s_addc_u32 s101, s31, 0
	global_load_dwordx4 v[160:163], v38, s[100:101]
	s_add_u32 s100, s30, 0x9000
	s_addc_u32 s101, s31, 0
	global_load_dwordx4 v[164:167], v38, s[100:101]
	s_add_u32 s100, s30, 0xc000
	s_addc_u32 s101, s31, 0
	global_load_dwordx4 v[114:117], v38, s[100:101]
	global_load_dwordx4 v[102:105], v38, s[34:35]
	s_add_u32 s100, s30, 0x12000
	s_addc_u32 s101, s31, 0
	global_load_dwordx4 v[110:113], v38, s[100:101]
	s_add_u32 s100, s34, 0x6000
	s_addc_u32 s101, s35, 0
	global_load_dwordx4 v[106:109], v38, s[100:101]
	s_add_u32 s100, s30, 0xf000
	s_addc_u32 s101, s31, 0
	global_load_dwordx4 v[126:129], v38, s[100:101]
	s_add_u32 s100, s30, 0x15000
	s_addc_u32 s101, s31, 0
	global_load_dwordx4 v[118:121], v38, s[100:101]
	s_add_u32 s100, s34, 0x3000
	s_addc_u32 s101, s35, 0
	global_load_dwordx4 v[130:133], v38, s[100:101]
	s_add_u32 s100, s34, 0x9000
	s_addc_u32 s101, s35, 0
	global_load_dwordx4 v[122:125], v38, s[100:101]
	s_add_u32 s100, s34, 0xc000
	s_addc_u32 s101, s35, 0
	global_load_dwordx4 v[98:101], v38, s[100:101]
	global_load_dwordx4 v[78:81], v38, s[24:25]
	s_add_u32 s100, s34, 0x12000
	s_addc_u32 s101, s35, 0
	global_load_dwordx4 v[94:97], v38, s[100:101]
	s_add_u32 s100, s24, 0x6000
	s_addc_u32 s101, s25, 0
	global_load_dwordx4 v[82:85], v38, s[100:101]
	s_add_u32 s100, s34, 0xf000
	s_addc_u32 s101, s35, 0
	global_load_dwordx4 v[90:93], v38, s[100:101]
	s_add_u32 s100, s34, 0x15000
	s_addc_u32 s101, s35, 0
	global_load_dwordx4 v[74:77], v38, s[100:101]
	s_add_u32 s100, s24, 0x3000
	s_addc_u32 s101, s25, 0
	global_load_dwordx4 v[86:89], v38, s[100:101]
	s_add_u32 s100, s24, 0x9000
	s_addc_u32 s101, s25, 0
	global_load_dwordx4 v[70:73], v38, s[100:101]
	s_add_u32 s100, s24, 0xc000
	s_addc_u32 s101, s25, 0
	global_load_dwordx4 v[62:65], v38, s[100:101]
	global_load_dwordx4 v[46:49], v38, s[36:37]
	s_add_u32 s100, s24, 0x12000
	s_addc_u32 s101, s25, 0
	global_load_dwordx4 v[54:57], v38, s[100:101]
	s_add_u32 s100, s36, 0x6000
	s_addc_u32 s101, s37, 0
	global_load_dwordx4 v[50:53], v38, s[100:101]
	s_add_u32 s100, s24, 0x15000
	s_addc_u32 s101, s25, 0
	global_load_dwordx4 v[42:45], v38, s[100:101]
	s_add_u32 s100, s24, 0xf000
	s_addc_u32 s101, s25, 0
	global_load_dwordx4 v[66:69], v38, s[100:101]
	s_add_u32 s100, s36, 0x3000
	s_addc_u32 s101, s37, 0
	global_load_dwordx4 v[58:61], v38, s[100:101]
	s_add_u32 s100, s36, 0x9000
	s_addc_u32 s101, s37, 0
	global_load_dwordx4 v[38:41], v38, s[100:101]
	s_mov_b32 s13, 0xc000
	s_nop 0
	s_mov_b32 s4, 0x12000
	s_nop 0
	s_nop 0
	s_movk_i32 s5, 0x6000
	s_nop 0
	s_mov_b32 s59, 0xf000
	s_nop 0
	s_mov_b32 s60, 0x15000
	s_nop 0
	s_movk_i32 s57, 0x3000
	s_nop 0
	s_mov_b32 s58, 0x9000
	s_nop 0
	s_waitcnt vmcnt(0) lgkmcnt(0)
	v_pk_fma_f32 v[142:143], v[26:27], v[142:143], v[30:31]
	v_pk_fma_f32 v[142:143], v[22:23], v[138:139], v[142:143]
	v_lshl_add_u64 v[158:159], v[2:3], 1, s[10:11]
	v_pk_fma_f32 v[142:143], v[18:19], v[154:155], v[142:143]
	v_pk_fma_f32 v[144:145], v[28:29], v[144:145], v[32:33]
	v_mul_f32_e32 v3, v142, v142
	v_fmamk_f32 v3, v3, 0xbdd2d3e2, v220
	v_mul_f32_e32 v5, v143, v143
	v_mul_f32_e32 v3, v142, v3
	v_fmamk_f32 v5, v5, 0xbdd2d3e2, v220
	v_exp_f32_e32 v3, v3
	v_mul_f32_e32 v5, v143, v5
	v_exp_f32_e32 v5, v5
	v_pk_fma_f32 v[144:145], v[24:25], v[140:141], v[144:145]
	v_pk_fma_f32 v[138:139], v[26:27], v[138:139], v[30:31]
	v_pk_fma_f32 v[144:145], v[20:21], v[156:157], v[144:145]
	v_pk_fma_f32 v[138:139], v[22:23], v[154:155], v[138:139]
	v_add_f32_e32 v3, 1.0, v3
	v_pk_fma_f32 v[138:139], v[18:19], v[150:151], v[138:139]
	v_rcp_f32_e32 v150, v3
	v_add_f32_e32 v3, 1.0, v5
	v_mul_f32_e32 v5, v144, v144
	v_fmamk_f32 v5, v5, 0xbdd2d3e2, v220
	v_mul_f32_e32 v151, v145, v145
	v_pk_fma_f32 v[140:141], v[28:29], v[140:141], v[32:33]
	v_mul_f32_e32 v5, v144, v5
	v_fmamk_f32 v151, v151, 0xbdd2d3e2, v220
	v_pk_fma_f32 v[140:141], v[24:25], v[156:157], v[140:141]
	v_exp_f32_e32 v5, v5
	v_mul_f32_e32 v151, v145, v151
	v_pk_fma_f32 v[140:141], v[20:21], v[152:153], v[140:141]
	v_exp_f32_e32 v153, v151
	v_rcp_f32_e32 v152, v3
	s_nop 0
	v_add_f32_e32 v3, 1.0, v5
	v_rcp_f32_e32 v151, v3
	v_add_f32_e32 v3, 1.0, v153
	v_rcp_f32_e32 v153, v3
	v_pk_fma_f32 v[136:137], v[12:13], v[136:137], v[36:37]
	v_pk_fma_f32 v[134:135], v[10:11], v[134:135], v[34:35]
	v_pk_fma_f32 v[136:137], v[16:17], v[148:149], v[136:137]
	v_pk_fma_f32 v[134:135], v[14:15], v[146:147], v[134:135]
	v_pk_fma_f32 v[136:137], v[8:9], v[162:163], v[136:137]
	v_pk_fma_f32 v[134:135], v[6:7], v[160:161], v[134:135]
	v_mov_b32_e32 v154, v142
	v_mov_b32_e32 v155, v144
	v_mov_b32_e32 v144, v143
	v_pk_mul_f32 v[150:151], v[154:155], v[150:151]
	v_mov_b32_e32 v155, v136
	v_pk_mul_f32 v[142:143], v[144:145], v[152:153]
	v_mov_b32_e32 v136, v135
	v_mov_b32_e32 v154, v134
	v_pk_mul_f32 v[134:135], v[142:143], v[136:137]
	v_pk_mul_f32 v[150:151], v[150:151], v[154:155]
	v_and_b32_sdwa v136, v135, v218 dst_sel:DWORD dst_unused:UNUSED_PAD src0_sel:WORD_1 src1_sel:DWORD
	v_and_b32_sdwa v3, v151, v218 dst_sel:DWORD dst_unused:UNUSED_PAD src0_sel:WORD_1 src1_sel:DWORD
	v_and_b32_sdwa v137, v134, v218 dst_sel:DWORD dst_unused:UNUSED_PAD src0_sel:WORD_1 src1_sel:DWORD
	v_add3_u32 v135, v135, v136, s91
	v_and_b32_sdwa v5, v150, v218 dst_sel:DWORD dst_unused:UNUSED_PAD src0_sel:WORD_1 src1_sel:DWORD
	v_add3_u32 v3, v151, v3, s91
	v_add3_u32 v134, v134, v137, s91
	v_and_b32_e32 v135, 0xffff0000, v135
	v_add3_u32 v5, v150, v5, s91
	v_and_b32_e32 v134, 0xffff0000, v134
	v_or_b32_sdwa v135, v135, v3 dst_sel:DWORD dst_unused:UNUSED_PAD src0_sel:DWORD src1_sel:WORD_1
	v_mul_f32_e32 v3, v138, v138
	v_or_b32_sdwa v134, v134, v5 dst_sel:DWORD dst_unused:UNUSED_PAD src0_sel:DWORD src1_sel:WORD_1
	v_fmamk_f32 v3, v3, 0xbdd2d3e2, v220
	v_mul_f32_e32 v5, v139, v139
	v_mul_f32_e32 v3, v138, v3
	v_fmamk_f32 v5, v5, 0xbdd2d3e2, v220
	v_exp_f32_e32 v3, v3
	v_mul_f32_e32 v5, v139, v5
	s_nop 0
	v_exp_f32_e32 v5, v5
	s_nop 0
	v_lshl_add_u64 v[136:137], v[158:159], 0, s[38:39]
	s_nop 0
	v_add_f32_e32 v3, 1.0, v3
	s_nop 0
	v_pk_fma_f32 v[148:149], v[12:13], v[148:149], v[36:37]
	global_store_dwordx2 v[136:137], v[134:135], off
	v_rcp_f32_e32 v134, v3
	v_add_f32_e32 v3, 1.0, v5
	v_mul_f32_e32 v5, v140, v140
	v_fmamk_f32 v5, v5, 0xbdd2d3e2, v220
	v_mul_f32_e32 v135, v141, v141
	v_mul_f32_e32 v5, v140, v5
	v_fmamk_f32 v135, v135, 0xbdd2d3e2, v220
	v_exp_f32_e32 v5, v5
	v_mul_f32_e32 v135, v141, v135
	v_exp_f32_e32 v137, v135
	v_rcp_f32_e32 v136, v3
	v_add_f32_e32 v3, 1.0, v5
	v_rcp_f32_e32 v135, v3
	v_add_f32_e32 v3, 1.0, v137
	v_pk_fma_f32 v[146:147], v[10:11], v[146:147], v[34:35]
	v_rcp_f32_e32 v137, v3
	v_pk_fma_f32 v[148:149], v[16:17], v[162:163], v[148:149]
	v_pk_fma_f32 v[146:147], v[14:15], v[160:161], v[146:147]
	v_pk_fma_f32 v[148:149], v[8:9], v[166:167], v[148:149]
	v_pk_fma_f32 v[146:147], v[6:7], v[164:165], v[146:147]
	v_mov_b32_e32 v142, v138
	v_mov_b32_e32 v143, v140
	v_pk_mul_f32 v[134:135], v[142:143], v[134:135]
	v_mov_b32_e32 v142, v146
	v_mov_b32_e32 v143, v148
	v_mov_b32_e32 v140, v139
	v_pk_mul_f32 v[134:135], v[134:135], v[142:143]
	v_pk_mul_f32 v[136:137], v[140:141], v[136:137]
	v_mov_b32_e32 v148, v147
	v_pk_mul_f32 v[136:137], v[136:137], v[148:149]
	v_and_b32_sdwa v5, v134, v218 dst_sel:DWORD dst_unused:UNUSED_PAD src0_sel:WORD_1 src1_sel:DWORD
	v_and_b32_sdwa v3, v135, v218 dst_sel:DWORD dst_unused:UNUSED_PAD src0_sel:WORD_1 src1_sel:DWORD
	v_add3_u32 v5, v134, v5, s91
	v_and_b32_sdwa v134, v137, v218 dst_sel:DWORD dst_unused:UNUSED_PAD src0_sel:WORD_1 src1_sel:DWORD
	v_pk_fma_f32 v[114:115], v[26:27], v[114:115], v[30:31]
	v_add3_u32 v3, v135, v3, s91
	v_and_b32_sdwa v135, v136, v218 dst_sel:DWORD dst_unused:UNUSED_PAD src0_sel:WORD_1 src1_sel:DWORD
	v_add3_u32 v134, v137, v134, s91
	v_pk_fma_f32 v[114:115], v[22:23], v[110:111], v[114:115]
	v_add3_u32 v135, v136, v135, s91
	v_and_b32_e32 v134, 0xffff0000, v134
	v_pk_fma_f32 v[114:115], v[18:19], v[102:103], v[114:115]
	v_and_b32_e32 v136, 0xffff0000, v135
	v_or_b32_sdwa v135, v134, v3 dst_sel:DWORD dst_unused:UNUSED_PAD src0_sel:DWORD src1_sel:WORD_1
	v_mul_f32_e32 v3, v114, v114
	v_or_b32_sdwa v134, v136, v5 dst_sel:DWORD dst_unused:UNUSED_PAD src0_sel:DWORD src1_sel:WORD_1
	v_fmamk_f32 v3, v3, 0xbdd2d3e2, v220
	v_mul_f32_e32 v5, v115, v115
	v_mul_f32_e32 v3, v114, v3
	v_fmamk_f32 v5, v5, 0xbdd2d3e2, v220
	v_exp_f32_e32 v3, v3
	v_mul_f32_e32 v5, v115, v5
	v_pk_fma_f32 v[116:117], v[28:29], v[116:117], v[32:33]
	v_exp_f32_e32 v5, v5
	v_pk_fma_f32 v[116:117], v[24:25], v[112:113], v[116:117]
	v_pk_fma_f32 v[112:113], v[28:29], v[112:113], v[32:33]
	v_pk_fma_f32 v[116:117], v[20:21], v[104:105], v[116:117]
	v_pk_fma_f32 v[104:105], v[24:25], v[104:105], v[112:113]
	v_add_f32_e32 v3, 1.0, v3
	v_pk_fma_f32 v[104:105], v[20:21], v[108:109], v[104:105]
	v_pk_fma_f32 v[108:109], v[10:11], v[126:127], v[34:35]
	v_pk_fma_f32 v[112:113], v[10:11], v[118:119], v[34:35]
	v_pk_fma_f32 v[108:109], v[14:15], v[118:119], v[108:109]
	v_rcp_f32_e32 v118, v3
	v_add_f32_e32 v3, 1.0, v5
	v_mul_f32_e32 v5, v116, v116
	v_pk_fma_f32 v[110:111], v[26:27], v[110:111], v[30:31]
	v_fmamk_f32 v5, v5, 0xbdd2d3e2, v220
	v_mul_f32_e32 v119, v117, v117
	v_pk_fma_f32 v[102:103], v[22:23], v[102:103], v[110:111]
	v_mul_f32_e32 v5, v116, v5
	v_fmamk_f32 v119, v119, 0xbdd2d3e2, v220
	v_pk_fma_f32 v[102:103], v[18:19], v[106:107], v[102:103]
	v_pk_fma_f32 v[106:107], v[12:13], v[128:129], v[36:37]
	v_exp_f32_e32 v5, v5
	v_mul_f32_e32 v119, v117, v119
	v_pk_fma_f32 v[106:107], v[16:17], v[120:121], v[106:107]
	v_pk_fma_f32 v[110:111], v[12:13], v[120:121], v[36:37]
	v_exp_f32_e32 v121, v119
	v_rcp_f32_e32 v120, v3
	v_add_f32_e32 v3, 1.0, v5
	v_rcp_f32_e32 v119, v3
	v_add_f32_e32 v3, 1.0, v121
	v_rcp_f32_e32 v121, v3
	s_waitcnt lgkmcnt(0)
	v_pk_fma_f32 v[112:113], v[14:15], v[130:131], v[112:113]
	v_pk_fma_f32 v[106:107], v[8:9], v[132:133], v[106:107]
	v_pk_fma_f32 v[108:109], v[6:7], v[130:131], v[108:109]
	v_pk_fma_f32 v[112:113], v[6:7], v[122:123], v[112:113]
	v_mov_b32_e32 v122, v114
	v_mov_b32_e32 v123, v116
	v_mov_b32_e32 v116, v115
	v_pk_mul_f32 v[118:119], v[122:123], v[118:119]
	v_mov_b32_e32 v123, v106
	v_pk_mul_f32 v[114:115], v[116:117], v[120:121]
	v_mov_b32_e32 v106, v109
	v_mov_b32_e32 v122, v108
	v_pk_mul_f32 v[106:107], v[106:107], v[114:115]
	v_pk_mul_f32 v[118:119], v[122:123], v[118:119]
	v_and_b32_sdwa v108, v107, v218 dst_sel:DWORD dst_unused:UNUSED_PAD src0_sel:WORD_1 src1_sel:DWORD
	v_and_b32_sdwa v3, v119, v218 dst_sel:DWORD dst_unused:UNUSED_PAD src0_sel:WORD_1 src1_sel:DWORD
	v_and_b32_sdwa v109, v106, v218 dst_sel:DWORD dst_unused:UNUSED_PAD src0_sel:WORD_1 src1_sel:DWORD
	v_add3_u32 v107, v107, v108, s91
	v_and_b32_sdwa v5, v118, v218 dst_sel:DWORD dst_unused:UNUSED_PAD src0_sel:WORD_1 src1_sel:DWORD
	v_add3_u32 v3, v119, v3, s91
	v_add3_u32 v106, v106, v109, s91
	v_and_b32_e32 v107, 0xffff0000, v107
	v_add3_u32 v5, v118, v5, s91
	v_and_b32_e32 v106, 0xffff0000, v106
	v_or_b32_sdwa v107, v107, v3 dst_sel:DWORD dst_unused:UNUSED_PAD src0_sel:DWORD src1_sel:WORD_1
	v_mul_f32_e32 v3, v102, v102
	v_or_b32_sdwa v106, v106, v5 dst_sel:DWORD dst_unused:UNUSED_PAD src0_sel:DWORD src1_sel:WORD_1
	v_fmamk_f32 v3, v3, 0xbdd2d3e2, v220
	v_mul_f32_e32 v5, v103, v103
	v_mul_f32_e32 v3, v102, v3
	v_fmamk_f32 v5, v5, 0xbdd2d3e2, v220
	v_exp_f32_e32 v3, v3
	v_mul_f32_e32 v5, v103, v5
	v_exp_f32_e32 v5, v5
	v_lshl_add_u64 v[108:109], v[158:159], 0, s[42:43]
	v_add_f32_e32 v3, 1.0, v3
	global_store_dwordx2 v[108:109], v[106:107], off
	v_rcp_f32_e32 v106, v3
	v_add_f32_e32 v3, 1.0, v5
	v_mul_f32_e32 v5, v104, v104
	v_fmamk_f32 v5, v5, 0xbdd2d3e2, v220
	v_mul_f32_e32 v107, v105, v105
	v_mul_f32_e32 v5, v104, v5
	v_fmamk_f32 v107, v107, 0xbdd2d3e2, v220
	v_exp_f32_e32 v5, v5
	v_mul_f32_e32 v107, v105, v107
	v_exp_f32_e32 v109, v107
	v_rcp_f32_e32 v108, v3
	v_add_f32_e32 v3, 1.0, v5
	v_rcp_f32_e32 v107, v3
	v_add_f32_e32 v3, 1.0, v109
	v_rcp_f32_e32 v109, v3
	v_pk_fma_f32 v[110:111], v[16:17], v[132:133], v[110:111]
	v_mov_b32_e32 v114, v102
	v_pk_fma_f32 v[110:111], v[8:9], v[124:125], v[110:111]
	v_mov_b32_e32 v115, v104
	v_mov_b32_e32 v104, v103
	v_pk_mul_f32 v[106:107], v[114:115], v[106:107]
	v_mov_b32_e32 v115, v110
	v_pk_mul_f32 v[102:103], v[104:105], v[108:109]
	v_mov_b32_e32 v110, v113
	v_mov_b32_e32 v114, v112
	v_pk_mul_f32 v[102:103], v[110:111], v[102:103]
	v_pk_mul_f32 v[106:107], v[114:115], v[106:107]
	v_and_b32_sdwa v104, v103, v218 dst_sel:DWORD dst_unused:UNUSED_PAD src0_sel:WORD_1 src1_sel:DWORD
	v_pk_fma_f32 v[98:99], v[26:27], v[98:99], v[30:31]
	v_and_b32_sdwa v3, v107, v218 dst_sel:DWORD dst_unused:UNUSED_PAD src0_sel:WORD_1 src1_sel:DWORD
	v_and_b32_sdwa v105, v102, v218 dst_sel:DWORD dst_unused:UNUSED_PAD src0_sel:WORD_1 src1_sel:DWORD
	v_add3_u32 v103, v103, v104, s91
	v_pk_fma_f32 v[98:99], v[22:23], v[94:95], v[98:99]
	v_and_b32_sdwa v5, v106, v218 dst_sel:DWORD dst_unused:UNUSED_PAD src0_sel:WORD_1 src1_sel:DWORD
	v_add3_u32 v3, v107, v3, s91
	v_add3_u32 v102, v102, v105, s91
	v_and_b32_e32 v103, 0xffff0000, v103
	v_pk_fma_f32 v[98:99], v[18:19], v[78:79], v[98:99]
	v_add3_u32 v5, v106, v5, s91
	v_and_b32_e32 v102, 0xffff0000, v102
	v_or_b32_sdwa v103, v103, v3 dst_sel:DWORD dst_unused:UNUSED_PAD src0_sel:DWORD src1_sel:WORD_1
	v_mul_f32_e32 v3, v98, v98
	v_or_b32_sdwa v102, v102, v5 dst_sel:DWORD dst_unused:UNUSED_PAD src0_sel:DWORD src1_sel:WORD_1
	v_fmamk_f32 v3, v3, 0xbdd2d3e2, v220
	v_mul_f32_e32 v5, v99, v99
	v_pk_fma_f32 v[100:101], v[28:29], v[100:101], v[32:33]
	v_mul_f32_e32 v3, v98, v3
	v_fmamk_f32 v5, v5, 0xbdd2d3e2, v220
	v_pk_fma_f32 v[100:101], v[24:25], v[96:97], v[100:101]
	v_pk_fma_f32 v[96:97], v[28:29], v[96:97], v[32:33]
	v_exp_f32_e32 v3, v3
	v_mul_f32_e32 v5, v99, v5
	v_pk_fma_f32 v[100:101], v[20:21], v[80:81], v[100:101]
	v_pk_fma_f32 v[80:81], v[24:25], v[80:81], v[96:97]
	v_exp_f32_e32 v5, v5
	v_pk_fma_f32 v[80:81], v[20:21], v[84:85], v[80:81]
	v_pk_fma_f32 v[84:85], v[10:11], v[90:91], v[34:35]
	v_pk_fma_f32 v[94:95], v[26:27], v[94:95], v[30:31]
	v_pk_fma_f32 v[84:85], v[14:15], v[74:75], v[84:85]
	v_pk_fma_f32 v[74:75], v[10:11], v[74:75], v[34:35]
	v_add_f32_e32 v3, 1.0, v3
	v_pk_fma_f32 v[74:75], v[14:15], v[86:87], v[74:75]
	v_pk_fma_f32 v[78:79], v[22:23], v[78:79], v[94:95]
	v_pk_fma_f32 v[70:71], v[6:7], v[70:71], v[74:75]
	v_rcp_f32_e32 v74, v3
	v_add_f32_e32 v3, 1.0, v5
	v_mul_f32_e32 v5, v100, v100
	v_pk_fma_f32 v[78:79], v[18:19], v[82:83], v[78:79]
	v_pk_fma_f32 v[82:83], v[12:13], v[92:93], v[36:37]
	v_fmamk_f32 v5, v5, 0xbdd2d3e2, v220
	v_mul_f32_e32 v75, v101, v101
	v_pk_fma_f32 v[82:83], v[16:17], v[76:77], v[82:83]
	v_pk_fma_f32 v[76:77], v[12:13], v[76:77], v[36:37]
	v_mul_f32_e32 v5, v100, v5
	v_fmamk_f32 v75, v75, 0xbdd2d3e2, v220
	v_pk_fma_f32 v[76:77], v[16:17], v[88:89], v[76:77]
	v_exp_f32_e32 v5, v5
	v_mul_f32_e32 v75, v101, v75
	v_pk_fma_f32 v[72:73], v[8:9], v[72:73], v[76:77]
	v_exp_f32_e32 v77, v75
	v_rcp_f32_e32 v76, v3
	v_add_f32_e32 v3, 1.0, v5
	v_rcp_f32_e32 v75, v3
	v_add_f32_e32 v3, 1.0, v77
	v_rcp_f32_e32 v77, v3
	v_pk_fma_f32 v[82:83], v[8:9], v[88:89], v[82:83]
	v_pk_fma_f32 v[84:85], v[6:7], v[86:87], v[84:85]
	v_mov_b32_e32 v86, v98
	v_mov_b32_e32 v87, v100
	v_pk_mul_f32 v[74:75], v[86:87], v[74:75]
	v_mov_b32_e32 v86, v84
	v_mov_b32_e32 v87, v82
	v_mov_b32_e32 v100, v99
	v_pk_mul_f32 v[74:75], v[86:87], v[74:75]
	v_pk_mul_f32 v[76:77], v[100:101], v[76:77]
	v_mov_b32_e32 v82, v85
	v_pk_mul_f32 v[76:77], v[82:83], v[76:77]
	v_and_b32_sdwa v5, v74, v218 dst_sel:DWORD dst_unused:UNUSED_PAD src0_sel:WORD_1 src1_sel:DWORD
	v_and_b32_sdwa v3, v75, v218 dst_sel:DWORD dst_unused:UNUSED_PAD src0_sel:WORD_1 src1_sel:DWORD
	v_add3_u32 v5, v74, v5, s91
	v_and_b32_sdwa v74, v77, v218 dst_sel:DWORD dst_unused:UNUSED_PAD src0_sel:WORD_1 src1_sel:DWORD
	v_add3_u32 v3, v75, v3, s91
	v_and_b32_sdwa v75, v76, v218 dst_sel:DWORD dst_unused:UNUSED_PAD src0_sel:WORD_1 src1_sel:DWORD
	v_add3_u32 v74, v77, v74, s91
	v_add3_u32 v75, v76, v75, s91
	v_and_b32_e32 v74, 0xffff0000, v74
	v_and_b32_e32 v76, 0xffff0000, v75
	v_or_b32_sdwa v75, v74, v3 dst_sel:DWORD dst_unused:UNUSED_PAD src0_sel:DWORD src1_sel:WORD_1
	v_mul_f32_e32 v3, v78, v78
	v_or_b32_sdwa v74, v76, v5 dst_sel:DWORD dst_unused:UNUSED_PAD src0_sel:DWORD src1_sel:WORD_1
	v_fmamk_f32 v3, v3, 0xbdd2d3e2, v220
	v_mul_f32_e32 v5, v79, v79
	v_mul_f32_e32 v3, v78, v3
	v_fmamk_f32 v5, v5, 0xbdd2d3e2, v220
	v_exp_f32_e32 v3, v3
	v_mul_f32_e32 v5, v79, v5
	v_exp_f32_e32 v5, v5
	v_lshl_add_u64 v[76:77], v[158:159], 0, s[46:47]
	v_add_f32_e32 v3, 1.0, v3
	global_store_dwordx2 v[76:77], v[74:75], off
	v_rcp_f32_e32 v74, v3
	v_add_f32_e32 v3, 1.0, v5
	v_mul_f32_e32 v5, v80, v80
	v_fmamk_f32 v5, v5, 0xbdd2d3e2, v220
	v_mul_f32_e32 v75, v81, v81
	v_mul_f32_e32 v5, v80, v5
	v_fmamk_f32 v75, v75, 0xbdd2d3e2, v220
	v_exp_f32_e32 v5, v5
	v_mul_f32_e32 v75, v81, v75
	v_exp_f32_e32 v77, v75
	v_rcp_f32_e32 v76, v3
	v_add_f32_e32 v3, 1.0, v5
	v_rcp_f32_e32 v75, v3
	v_add_f32_e32 v3, 1.0, v77
	v_rcp_f32_e32 v77, v3
	v_mov_b32_e32 v82, v78
	v_mov_b32_e32 v83, v80
	v_mov_b32_e32 v80, v79
	v_pk_mul_f32 v[74:75], v[82:83], v[74:75]
	v_mov_b32_e32 v83, v72
	v_pk_mul_f32 v[76:77], v[80:81], v[76:77]
	v_mov_b32_e32 v72, v71
	v_mov_b32_e32 v82, v70
	v_pk_mul_f32 v[70:71], v[72:73], v[76:77]
	v_pk_mul_f32 v[74:75], v[82:83], v[74:75]
	v_and_b32_sdwa v72, v71, v218 dst_sel:DWORD dst_unused:UNUSED_PAD src0_sel:WORD_1 src1_sel:DWORD
	v_pk_fma_f32 v[62:63], v[26:27], v[62:63], v[30:31]
	v_and_b32_sdwa v3, v75, v218 dst_sel:DWORD dst_unused:UNUSED_PAD src0_sel:WORD_1 src1_sel:DWORD
	v_and_b32_sdwa v73, v70, v218 dst_sel:DWORD dst_unused:UNUSED_PAD src0_sel:WORD_1 src1_sel:DWORD
	v_add3_u32 v71, v71, v72, s91
	v_pk_fma_f32 v[62:63], v[22:23], v[54:55], v[62:63]
	v_and_b32_sdwa v5, v74, v218 dst_sel:DWORD dst_unused:UNUSED_PAD src0_sel:WORD_1 src1_sel:DWORD
	v_add3_u32 v3, v75, v3, s91
	v_add3_u32 v70, v70, v73, s91
	v_and_b32_e32 v71, 0xffff0000, v71
	v_pk_fma_f32 v[62:63], v[18:19], v[46:47], v[62:63]
	v_add3_u32 v5, v74, v5, s91
	v_and_b32_e32 v70, 0xffff0000, v70
	v_or_b32_sdwa v71, v71, v3 dst_sel:DWORD dst_unused:UNUSED_PAD src0_sel:DWORD src1_sel:WORD_1
	v_mul_f32_e32 v3, v62, v62
	v_or_b32_sdwa v70, v70, v5 dst_sel:DWORD dst_unused:UNUSED_PAD src0_sel:DWORD src1_sel:WORD_1
	v_fmamk_f32 v3, v3, 0xbdd2d3e2, v220
	v_mul_f32_e32 v5, v63, v63
	v_mul_f32_e32 v3, v62, v3
	v_fmamk_f32 v5, v5, 0xbdd2d3e2, v220
	v_exp_f32_e32 v3, v3
	v_mul_f32_e32 v5, v63, v5
	v_pk_fma_f32 v[64:65], v[28:29], v[64:65], v[32:33]
	v_pk_fma_f32 v[28:29], v[28:29], v[56:57], v[32:33]
	v_exp_f32_e32 v5, v5
	v_pk_fma_f32 v[64:65], v[24:25], v[56:57], v[64:65]
	v_pk_fma_f32 v[24:25], v[24:25], v[48:49], v[28:29]
	v_pk_fma_f32 v[64:65], v[20:21], v[48:49], v[64:65]
	v_pk_fma_f32 v[20:21], v[20:21], v[52:53], v[24:25]
	v_pk_fma_f32 v[24:25], v[10:11], v[66:67], v[34:35]
	v_pk_fma_f32 v[10:11], v[10:11], v[42:43], v[34:35]
	v_pk_fma_f32 v[24:25], v[14:15], v[42:43], v[24:25]
	v_pk_fma_f32 v[10:11], v[14:15], v[58:59], v[10:11]
	v_add_f32_e32 v3, 1.0, v3
	v_pk_fma_f32 v[26:27], v[26:27], v[54:55], v[30:31]
	v_pk_fma_f32 v[24:25], v[6:7], v[58:59], v[24:25]
	v_pk_fma_f32 v[6:7], v[6:7], v[38:39], v[10:11]
	v_rcp_f32_e32 v10, v3
	v_add_f32_e32 v3, 1.0, v5
	v_mul_f32_e32 v5, v64, v64
	v_pk_fma_f32 v[22:23], v[22:23], v[46:47], v[26:27]
	v_fmamk_f32 v5, v5, 0xbdd2d3e2, v220
	v_mul_f32_e32 v11, v65, v65
	v_pk_fma_f32 v[18:19], v[18:19], v[50:51], v[22:23]
	v_pk_fma_f32 v[22:23], v[12:13], v[68:69], v[36:37]
	v_pk_fma_f32 v[12:13], v[12:13], v[44:45], v[36:37]
	v_mul_f32_e32 v5, v64, v5
	v_fmamk_f32 v11, v11, 0xbdd2d3e2, v220
	v_pk_fma_f32 v[22:23], v[16:17], v[44:45], v[22:23]
	v_pk_fma_f32 v[12:13], v[16:17], v[60:61], v[12:13]
	v_exp_f32_e32 v5, v5
	v_mul_f32_e32 v11, v65, v11
	v_pk_fma_f32 v[22:23], v[8:9], v[60:61], v[22:23]
	v_pk_fma_f32 v[8:9], v[8:9], v[40:41], v[12:13]
	v_exp_f32_e32 v13, v11
	v_rcp_f32_e32 v12, v3
	v_add_f32_e32 v3, 1.0, v5
	v_rcp_f32_e32 v11, v3
	v_add_f32_e32 v3, 1.0, v13
	v_rcp_f32_e32 v13, v3
	v_mov_b32_e32 v14, v62
	v_mov_b32_e32 v15, v64
	v_pk_mul_f32 v[10:11], v[14:15], v[10:11]
	v_mov_b32_e32 v14, v24
	v_mov_b32_e32 v15, v22
	v_mov_b32_e32 v64, v63
	v_pk_mul_f32 v[10:11], v[14:15], v[10:11]
	v_pk_mul_f32 v[12:13], v[64:65], v[12:13]
	v_mov_b32_e32 v22, v25
	v_pk_mul_f32 v[12:13], v[22:23], v[12:13]
	v_and_b32_sdwa v5, v10, v218 dst_sel:DWORD dst_unused:UNUSED_PAD src0_sel:WORD_1 src1_sel:DWORD
	v_and_b32_sdwa v3, v11, v218 dst_sel:DWORD dst_unused:UNUSED_PAD src0_sel:WORD_1 src1_sel:DWORD
	v_add3_u32 v5, v10, v5, s91
	v_and_b32_sdwa v10, v13, v218 dst_sel:DWORD dst_unused:UNUSED_PAD src0_sel:WORD_1 src1_sel:DWORD
	v_add3_u32 v3, v11, v3, s91
	v_and_b32_sdwa v11, v12, v218 dst_sel:DWORD dst_unused:UNUSED_PAD src0_sel:WORD_1 src1_sel:DWORD
	v_add3_u32 v10, v13, v10, s91
	v_add3_u32 v11, v12, v11, s91
	v_and_b32_e32 v10, 0xffff0000, v10
	v_and_b32_e32 v12, 0xffff0000, v11
	v_or_b32_sdwa v11, v10, v3 dst_sel:DWORD dst_unused:UNUSED_PAD src0_sel:DWORD src1_sel:WORD_1
	v_mul_f32_e32 v3, v18, v18
	v_or_b32_sdwa v10, v12, v5 dst_sel:DWORD dst_unused:UNUSED_PAD src0_sel:DWORD src1_sel:WORD_1
	v_fmamk_f32 v3, v3, 0xbdd2d3e2, v220
	v_mul_f32_e32 v5, v19, v19
	v_mul_f32_e32 v3, v18, v3
	v_fmamk_f32 v5, v5, 0xbdd2d3e2, v220
	v_exp_f32_e32 v3, v3
	v_mul_f32_e32 v5, v19, v5
	v_exp_f32_e32 v5, v5
	v_lshl_add_u64 v[12:13], v[158:159], 0, s[50:51]
	v_add_f32_e32 v3, 1.0, v3
	global_store_dwordx2 v[12:13], v[10:11], off
	v_rcp_f32_e32 v10, v3
	v_add_f32_e32 v3, 1.0, v5
	v_mul_f32_e32 v5, v20, v20
	v_fmamk_f32 v5, v5, 0xbdd2d3e2, v220
	v_mul_f32_e32 v11, v21, v21
	v_mul_f32_e32 v5, v20, v5
	v_fmamk_f32 v11, v11, 0xbdd2d3e2, v220
	v_exp_f32_e32 v5, v5
	v_mul_f32_e32 v11, v21, v11
	v_exp_f32_e32 v13, v11
	v_rcp_f32_e32 v12, v3
	v_add_f32_e32 v3, 1.0, v5
	v_rcp_f32_e32 v11, v3
	v_add_f32_e32 v3, 1.0, v13
	v_rcp_f32_e32 v13, v3
	v_mov_b32_e32 v14, v18
	v_mov_b32_e32 v15, v20
	v_mov_b32_e32 v20, v19
	v_pk_mul_f32 v[10:11], v[14:15], v[10:11]
	v_mov_b32_e32 v15, v8
	v_pk_mul_f32 v[12:13], v[20:21], v[12:13]
	v_mov_b32_e32 v8, v7
	v_mov_b32_e32 v14, v6
	v_pk_mul_f32 v[6:7], v[8:9], v[12:13]
	v_pk_mul_f32 v[10:11], v[14:15], v[10:11]
	v_and_b32_sdwa v8, v7, v218 dst_sel:DWORD dst_unused:UNUSED_PAD src0_sel:WORD_1 src1_sel:DWORD
	v_and_b32_sdwa v9, v6, v218 dst_sel:DWORD dst_unused:UNUSED_PAD src0_sel:WORD_1 src1_sel:DWORD
	v_and_b32_sdwa v3, v11, v218 dst_sel:DWORD dst_unused:UNUSED_PAD src0_sel:WORD_1 src1_sel:DWORD
	v_and_b32_sdwa v5, v10, v218 dst_sel:DWORD dst_unused:UNUSED_PAD src0_sel:WORD_1 src1_sel:DWORD
	v_add3_u32 v7, v7, v8, s91
	v_add3_u32 v6, v6, v9, s91
	v_add_u32_e32 v0, 0x200, v0
	v_add3_u32 v5, v10, v5, s91
	v_add3_u32 v3, v11, v3, s91
	v_and_b32_e32 v7, 0xffff0000, v7
	v_and_b32_e32 v6, 0xffff0000, v6
	v_cmp_lt_i32_e32 vcc, s66, v0
	v_lshl_add_u64 v[136:137], v[158:159], 0, s[40:41]
	v_lshl_add_u64 v[104:105], v[158:159], 0, s[44:45]
	v_lshl_add_u64 v[72:73], v[158:159], 0, s[48:49]
	v_or_b32_sdwa v7, v7, v3 dst_sel:DWORD dst_unused:UNUSED_PAD src0_sel:DWORD src1_sel:WORD_1
	v_or_b32_sdwa v6, v6, v5 dst_sel:DWORD dst_unused:UNUSED_PAD src0_sel:DWORD src1_sel:WORD_1
	v_lshl_add_u64 v[8:9], v[158:159], 0, s[52:53]
	s_or_b64 s[54:55], vcc, s[54:55]
	v_add_u32_e32 v2, 0x800, v2
	global_store_dwordx2 v[136:137], v[134:135], off
	global_store_dwordx2 v[104:105], v[102:103], off
	global_store_dwordx2 v[72:73], v[70:71], off
	global_store_dwordx2 v[8:9], v[6:7], off
	s_andn2_b64 exec, exec, s[54:55]
	s_cbranch_execz .LBB0_294
